# HGRN phase C chunk loop: batch serialized LDS reads in prefix-sum stage and ST image stage
# speedup vs baseline: 1.0093x; 1.0093x over previous
.LBB0_728:
	v_lshlrev_b32_e32 v64, 16, v60
	v_and_b32_e32 v65, 0xffff0000, v60
	v_lshlrev_b32_e32 v66, 16, v61
	v_and_b32_e32 v67, 0xffff0000, v61
	v_lshlrev_b32_e32 v60, 16, v62
	v_and_b32_e32 v61, 0xffff0000, v62
	v_lshlrev_b32_e32 v62, 16, v63
	v_and_b32_e32 v63, 0xffff0000, v63
	ds_write_b128 v73, v[64:67]
	ds_write_b128 v73, v[60:63] offset:16
	ds_write_b16 v79, v68 offset:60672
	ds_write_b16_d16_hi v79, v68 offset:60752
	ds_write_b16 v79, v69 offset:60832
	ds_write_b16_d16_hi v79, v69 offset:60912
	ds_write_b16 v79, v70 offset:60992
	ds_write_b16_d16_hi v79, v70 offset:61072
	ds_write_b16 v79, v71 offset:61152
	ds_write_b16_d16_hi v79, v71 offset:61232
	s_waitcnt lgkmcnt(0)
	s_barrier
	s_and_b64 vcc, exec, s[22:23]
	s_mov_b64 s[90:91], -1
	s_cbranch_vccnz .LBB0_734
	v_mov_b32_e32 v0, 0
	s_and_saveexec_b64 s[90:91], s[8:9]
	s_cbranch_execz .LBB0_733
	v_mov_b32_e32 v0, 0
	v_readfirstlane_b32 s28, v85
	v_add_u32_e32 v2, 0x1000, v87
	ds_read_b32 v206, v2 offset:11776
	ds_read_b32 v207, v2 offset:11264
	ds_read_b32 v208, v2 offset:10752
	ds_read_b32 v209, v2 offset:10240
	ds_read_b32 v210, v2 offset:9728
	ds_read_b32 v211, v2 offset:9216
	ds_read_b32 v212, v2 offset:8704
	ds_read_b32 v213, v2 offset:8192
	s_cmp_gt_u32 s28, 16
	s_cbranch_scc1 .Lhc_preA_w
	ds_read_b32 v214, v2 offset:7680
	ds_read_b32 v215, v2 offset:7168
	ds_read_b32 v216, v2 offset:6656
	ds_read_b32 v217, v2 offset:6144
	ds_read_b32 v218, v2 offset:5632
	ds_read_b32 v219, v2 offset:5120
	ds_read_b32 v220, v2 offset:4608
	ds_read_b32 v221, v2 offset:4096
	s_cmp_gt_u32 s28, 8
	s_cbranch_scc1 .Lhc_preA_w
	ds_read_b32 v222, v2 offset:3584
	ds_read_b32 v223, v2 offset:3072
	ds_read_b32 v224, v2 offset:2560
	ds_read_b32 v225, v2 offset:2048
	ds_read_b32 v226, v2 offset:1536
	ds_read_b32 v227, v2 offset:1024
	ds_read_b32 v228, v2 offset:512
	ds_read_b32 v229, v2 offset:0
.Lhc_preA_w:
	s_waitcnt lgkmcnt(0)
	v_add_f32_e32 v0, v0, v206
	v_add_f32_e32 v0, v0, v207
	v_add_f32_e32 v0, v0, v208
	v_add_f32_e32 v0, v0, v209
	v_add_f32_e32 v0, v0, v210
	v_add_f32_e32 v0, v0, v211
	v_add_f32_e32 v0, v0, v212
	v_add_f32_e32 v0, v0, v213
	s_cmp_gt_u32 s28, 16
	s_cbranch_scc1 .LBB0_733
	v_add_f32_e32 v0, v0, v214
	v_add_f32_e32 v0, v0, v215
	v_add_f32_e32 v0, v0, v216
	v_add_f32_e32 v0, v0, v217
	v_add_f32_e32 v0, v0, v218
	v_add_f32_e32 v0, v0, v219
	v_add_f32_e32 v0, v0, v220
	v_add_f32_e32 v0, v0, v221
	s_cmp_gt_u32 s28, 8
	s_cbranch_scc1 .LBB0_733
	v_add_f32_e32 v0, v0, v222
	v_add_f32_e32 v0, v0, v223
	v_add_f32_e32 v0, v0, v224
	v_add_f32_e32 v0, v0, v225
	v_add_f32_e32 v0, v0, v226
	v_add_f32_e32 v0, v0, v227
	v_add_f32_e32 v0, v0, v228
	v_add_f32_e32 v0, v0, v229
.LBB0_733:
	s_or_b64 exec, exec, s[90:91]
	ds_read2st64_b32 v[230:231], v117 offset0:12 offset1:14
	ds_read2st64_b32 v[232:233], v117 offset0:8 offset1:10
	ds_read2st64_b32 v[234:235], v117 offset0:4 offset1:6
	ds_read2st64_b32 v[236:237], v117 offset1:2
	s_mov_b64 s[90:91], 0
	s_waitcnt lgkmcnt(0)
	v_add_f32_e32 v0, v0, v231
	v_add_f32_e32 v68, v0, v230
	ds_write2st64_b32 v117, v68, v0 offset0:76 offset1:78
	v_add_f32_e32 v0, v68, v233
	v_add_f32_e32 v68, v0, v232
	ds_write2st64_b32 v117, v68, v0 offset0:72 offset1:74
	v_add_f32_e32 v0, v68, v235
	v_add_f32_e32 v68, v0, v234
	ds_write2st64_b32 v117, v68, v0 offset0:68 offset1:70
	v_add_f32_e32 v3, v68, v237
	v_add_f32_e32 v0, v3, v236
	ds_write2st64_b32 v117, v0, v3 offset0:64 offset1:66
.LBB0_734:
	s_mov_b32 s28, 2
	s_and_b64 vcc, exec, s[90:91]
	s_cbranch_vccz .LBB0_740
	v_mov_b32_e32 v0, 0
	s_and_saveexec_b64 s[90:91], s[10:11]
	s_cbranch_execz .LBB0_739
	v_mov_b32_e32 v0, 0
	v_readfirstlane_b32 s28, v83
	ds_read_b32 v206, v87
	ds_read_b32 v207, v87 offset:512
	ds_read_b32 v208, v87 offset:1024
	ds_read_b32 v209, v87 offset:1536
	ds_read_b32 v210, v87 offset:2048
	ds_read_b32 v211, v87 offset:2560
	ds_read_b32 v212, v87 offset:3072
	ds_read_b32 v213, v87 offset:3584
	s_cmp_lt_u32 s28, 16
	s_cbranch_scc1 .Lhc_preB_w
	ds_read_b32 v214, v87 offset:4096
	ds_read_b32 v215, v87 offset:4608
	ds_read_b32 v216, v87 offset:5120
	ds_read_b32 v217, v87 offset:5632
	ds_read_b32 v218, v87 offset:6144
	ds_read_b32 v219, v87 offset:6656
	ds_read_b32 v220, v87 offset:7168
	ds_read_b32 v221, v87 offset:7680
	s_cmp_lt_u32 s28, 24
	s_cbranch_scc1 .Lhc_preB_w
	ds_read_b32 v222, v87 offset:8192
	ds_read_b32 v223, v87 offset:8704
	ds_read_b32 v224, v87 offset:9216
	ds_read_b32 v225, v87 offset:9728
	ds_read_b32 v226, v87 offset:10240
	ds_read_b32 v227, v87 offset:10752
	ds_read_b32 v228, v87 offset:11264
	ds_read_b32 v229, v87 offset:11776
.Lhc_preB_w:
	s_waitcnt lgkmcnt(0)
	v_add_f32_e32 v0, v0, v206
	v_add_f32_e32 v0, v0, v207
	v_add_f32_e32 v0, v0, v208
	v_add_f32_e32 v0, v0, v209
	v_add_f32_e32 v0, v0, v210
	v_add_f32_e32 v0, v0, v211
	v_add_f32_e32 v0, v0, v212
	v_add_f32_e32 v0, v0, v213
	s_cmp_lt_u32 s28, 16
	s_cbranch_scc1 .LBB0_739
	v_add_f32_e32 v0, v0, v214
	v_add_f32_e32 v0, v0, v215
	v_add_f32_e32 v0, v0, v216
	v_add_f32_e32 v0, v0, v217
	v_add_f32_e32 v0, v0, v218
	v_add_f32_e32 v0, v0, v219
	v_add_f32_e32 v0, v0, v220
	v_add_f32_e32 v0, v0, v221
	s_cmp_lt_u32 s28, 24
	s_cbranch_scc1 .LBB0_739
	v_add_f32_e32 v0, v0, v222
	v_add_f32_e32 v0, v0, v223
	v_add_f32_e32 v0, v0, v224
	v_add_f32_e32 v0, v0, v225
	v_add_f32_e32 v0, v0, v226
	v_add_f32_e32 v0, v0, v227
	v_add_f32_e32 v0, v0, v228
	v_add_f32_e32 v0, v0, v229
.LBB0_739:
	s_or_b64 exec, exec, s[90:91]
	ds_read2st64_b32 v[230:231], v117 offset1:2
	ds_read2st64_b32 v[232:233], v117 offset0:4 offset1:6
	ds_read2st64_b32 v[234:235], v117 offset0:8 offset1:10
	ds_read_b32 v236, v117 offset:3072
	ds_read_b32 v237, v121
	s_mov_b32 s28, 1
	s_waitcnt lgkmcnt(0)
	v_add_f32_e32 v0, v0, v230
	v_add_f32_e32 v68, v0, v231
	ds_write2st64_b32 v117, v0, v68 offset0:64 offset1:66
	v_add_f32_e32 v0, v68, v232
	v_add_f32_e32 v68, v0, v233
	ds_write2st64_b32 v117, v0, v68 offset0:68 offset1:70
	v_add_f32_e32 v0, v68, v234
	v_add_f32_e32 v2, v0, v235
	ds_write2st64_b32 v117, v0, v2 offset0:72 offset1:74
	v_add_f32_e32 v0, v2, v236
	ds_write_b32 v117, v0 offset:19456
	v_add_f32_e32 v0, v0, v237
	ds_write_b32 v121, v0 offset:16384
.LBB0_740:
	v_mul_f32_e32 v0, 0x3fb8aa3b, v0
	v_exp_f32_e32 v0, v0
	v_cmp_eq_u32_e32 vcc, s28, v81
	s_and_saveexec_b64 s[90:91], vcc
	ds_write_b32 v89, v0
	s_or_b64 exec, exec, s[90:91]
	s_and_saveexec_b64 s[90:91], s[24:25]
	ds_write_b32 v91, v0
	s_or_b64 exec, exec, s[90:91]
	s_waitcnt lgkmcnt(0)
	s_barrier
	ds_read_b128 v[68:71], v73 offset:16384
	ds_read_b128 v[168:171], v73 offset:16400
	ds_read_b128 v[172:175], v115 offset:16384
	ds_read_b128 v[176:179], v115 offset:16400
	ds_read_b128 v[196:199], v161 offset:16384
	ds_read_b128 v[200:203], v161 offset:16400
	v_mul_f32_e32 v0, 0x3fb8aa3b, v64
	v_exp_f32_e32 v2, v0
	s_waitcnt lgkmcnt(3)
	v_sub_f32_e32 v0, v68, v172
	v_lshlrev_b32_e32 v204, 16, v56
	v_and_b32_e32 v205, 0xffff0000, v56
	v_sub_f32_e32 v56, v173, v69
	v_mul_f32_e32 v0, 0x3fb8aa3b, v0
	v_mul_f32_e32 v56, 0x3fb8aa3b, v56
	v_exp_f32_e32 v64, v0
	v_sub_f32_e32 v0, v172, v68
	v_mul_f32_e32 v3, 0x3fb8aa3b, v65
	v_sub_f32_e32 v65, v69, v173
	v_exp_f32_e32 v173, v56
	s_waitcnt lgkmcnt(1)
	v_sub_f32_e32 v56, v197, v69
	v_mul_f32_e32 v0, 0x3fb8aa3b, v0
	v_exp_f32_e32 v3, v3
	v_mul_f32_e32 v56, 0x3fb8aa3b, v56
	v_exp_f32_e32 v172, v0
	v_sub_f32_e32 v0, v196, v68
	v_exp_f32_e32 v56, v56
	v_mul_f32_e32 v0, 0x3fb8aa3b, v0
	v_exp_f32_e32 v0, v0
	v_pk_add_f32 v[2:3], v[2:3], 1.0 op_sel_hi:[1,0] neg_lo:[1,0] neg_hi:[1,0]
	v_mul_f32_e32 v65, 0x3fb8aa3b, v65
	v_pk_mul_f32 v[68:69], v[2:3], v[172:173]
	v_mul_f32_e32 v163, v3, v56
	v_sub_f32_e32 v3, v70, v174
	v_mul_f32_e32 v3, 0x3fb8aa3b, v3
	v_mul_f32_e32 v0, v2, v0
	v_mul_f32_e32 v2, 0x3fb8aa3b, v66
	v_exp_f32_e32 v66, v3
	v_sub_f32_e32 v3, v174, v70
	v_mul_f32_e32 v3, 0x3fb8aa3b, v3
	v_exp_f32_e32 v56, v3
	v_sub_f32_e32 v3, v198, v70
	v_mul_f32_e32 v3, 0x3fb8aa3b, v3
	v_exp_f32_e32 v70, v3
	v_mul_f32_e32 v3, 0x3fb8aa3b, v67
	v_sub_f32_e32 v67, v71, v175
	v_lshlrev_b32_e32 v172, 16, v57
	v_and_b32_e32 v173, 0xffff0000, v57
	v_sub_f32_e32 v57, v175, v71
	v_sub_f32_e32 v71, v199, v71
	v_exp_f32_e32 v2, v2
	v_exp_f32_e32 v3, v3
	v_mul_f32_e32 v57, 0x3fb8aa3b, v57
	v_mul_f32_e32 v71, 0x3fb8aa3b, v71
	v_exp_f32_e32 v57, v57
	v_exp_f32_e32 v166, v71
	v_pk_add_f32 v[2:3], v[2:3], 1.0 op_sel_hi:[1,0] neg_lo:[1,0] neg_hi:[1,0]
	v_mul_f32_e32 v67, 0x3fb8aa3b, v67
	v_mul_f32_e32 v174, v2, v70
	v_pk_mul_f32 v[70:71], v[2:3], v[56:57]
	v_mul_f32_e32 v166, v3, v166
	v_sub_f32_e32 v3, v168, v176
	v_sub_f32_e32 v57, v169, v177
	v_exp_f32_e32 v67, v67
	v_mul_f32_e32 v3, 0x3fb8aa3b, v3
	v_mul_f32_e32 v57, 0x3fb8aa3b, v57
	v_exp_f32_e32 v56, v3
	v_exp_f32_e32 v57, v57
	v_sub_f32_e32 v3, v176, v168
	v_pk_mul_f32 v[66:67], v[66:67], v[172:173]
	v_mul_f32_e32 v3, 0x3fb8aa3b, v3
	v_lshlrev_b32_e32 v172, 16, v58
	v_and_b32_e32 v173, 0xffff0000, v58
	v_mul_f32_e32 v2, 0x3fb8aa3b, v60
	v_exp_f32_e32 v60, v3
	s_waitcnt lgkmcnt(0)
	v_sub_f32_e32 v3, v200, v168
	v_pk_mul_f32 v[172:173], v[56:57], v[172:173]
	v_sub_f32_e32 v56, v177, v169
	v_mul_f32_e32 v3, 0x3fb8aa3b, v3
	v_mul_f32_e32 v56, 0x3fb8aa3b, v56
	v_exp_f32_e32 v168, v3
	v_mul_f32_e32 v3, 0x3fb8aa3b, v61
	v_exp_f32_e32 v61, v56
	v_sub_f32_e32 v56, v201, v169
	v_exp_f32_e32 v2, v2
	v_exp_f32_e32 v3, v3
	v_mul_f32_e32 v56, 0x3fb8aa3b, v56
	v_exp_f32_e32 v56, v56
	v_sub_f32_e32 v57, v171, v179
	v_pk_add_f32 v[2:3], v[2:3], 1.0 op_sel_hi:[1,0] neg_lo:[1,0] neg_hi:[1,0]
	v_mul_f32_e32 v57, 0x3fb8aa3b, v57
	v_pk_mul_f32 v[60:61], v[2:3], v[60:61]
	v_mul_f32_e32 v176, v3, v56
	v_sub_f32_e32 v3, v170, v178
	v_mul_f32_e32 v3, 0x3fb8aa3b, v3
	v_exp_f32_e32 v56, v3
	v_sub_f32_e32 v3, v178, v170
	v_mul_f32_e32 v3, 0x3fb8aa3b, v3
	v_exp_f32_e32 v57, v57
	v_exp_f32_e32 v58, v3
	v_sub_f32_e32 v3, v202, v170
	v_mul_f32_e32 v3, 0x3fb8aa3b, v3
	v_mul_f32_e32 v175, v2, v168
	v_mul_f32_e32 v2, 0x3fb8aa3b, v62
	v_exp_f32_e32 v168, v3
	v_mul_f32_e32 v3, 0x3fb8aa3b, v63
	v_lshlrev_b32_e32 v62, 16, v59
	v_and_b32_e32 v63, 0xffff0000, v59
	v_pk_mul_f32 v[62:63], v[56:57], v[62:63]
	v_sub_f32_e32 v56, v179, v171
	v_mul_f32_e32 v56, 0x3fb8aa3b, v56
	v_exp_f32_e32 v59, v56
	v_sub_f32_e32 v56, v203, v171
	v_exp_f32_e32 v65, v65
	v_exp_f32_e32 v2, v2
	v_exp_f32_e32 v3, v3
	v_mul_f32_e32 v56, 0x3fb8aa3b, v56
	v_exp_f32_e32 v56, v56
	v_pk_mul_f32 v[64:65], v[64:65], v[204:205]
	v_pk_add_f32 v[2:3], v[2:3], 1.0 op_sel_hi:[1,0] neg_lo:[1,0] neg_hi:[1,0]
	v_cvt_pk_bf16_f32 v57, v66, v67
	v_mul_f32_e32 v170, v2, v168
	v_pk_mul_f32 v[168:169], v[2:3], v[58:59]
	v_mul_f32_e32 v2, v3, v56
	v_cvt_pk_bf16_f32 v56, v64, v65
	v_cvt_pk_bf16_f32 v58, v172, v173
	v_cvt_pk_bf16_f32 v59, v62, v63
	ds_write_b128 v95, v[56:59] offset:32768
	v_cvt_pk_bf16_f32 v56, v68, v69
	v_cvt_pk_bf16_f32 v57, v70, v71
	v_cvt_pk_bf16_f32 v58, v60, v61
	v_cvt_pk_bf16_f32 v59, v168, v169
	v_cvt_pk_bf16_f32 v0, v0, s0
	ds_write_b128 v95, v[56:59] offset:41472
	ds_write_b16 v79, v0 offset:50176
	v_cvt_pk_bf16_f32 v0, v163, s0
	ds_write_b16 v79, v0 offset:50256
	v_cvt_pk_bf16_f32 v0, v174, s0
	ds_write_b16 v79, v0 offset:50336
	v_cvt_pk_bf16_f32 v0, v166, s0
	ds_write_b16 v79, v0 offset:50416
	v_cvt_pk_bf16_f32 v0, v175, s0
	ds_write_b16 v79, v0 offset:50496
	v_cvt_pk_bf16_f32 v0, v176, s0
	ds_write_b16 v79, v0 offset:50576
	v_cvt_pk_bf16_f32 v0, v170, s0
	ds_write_b16 v79, v0 offset:50656
	v_cvt_pk_bf16_f32 v0, v2, s0
	ds_write_b16 v79, v0 offset:50736
	ds_read_b128 v[206:209], v97
	ds_read_b128 v[210:213], v97 offset:64
	ds_read_b128 v[214:217], v97 offset:128
	ds_read_b128 v[218:221], v97 offset:192
	ds_read_b128 v[222:225], v97 offset:256
	ds_read_b128 v[226:229], v97 offset:320
	ds_read_b128 v[230:233], v97 offset:384
	ds_read_b128 v[234:237], v97 offset:448
	v_add_u32_e32 v0, v103, v99
	s_waitcnt lgkmcnt(7)
	v_pk_mul_f32 v[2:3], v[4:5], v[206:207]
	v_pk_mul_f32 v[56:57], v[6:7], v[208:209]
	v_cvt_pk_bf16_f32 v2, v2, v3
	v_cvt_pk_bf16_f32 v3, v56, v57
	ds_write_b64 v103, v[2:3]
	s_waitcnt lgkmcnt(7)
	v_pk_mul_f32 v[238:239], v[16:17], v[210:211]
	v_pk_mul_f32 v[240:241], v[18:19], v[212:213]
	v_cvt_pk_bf16_f32 v238, v238, v239
	v_cvt_pk_bf16_f32 v239, v240, v241
	ds_write_b64 v103, v[238:239] offset:32
	s_waitcnt lgkmcnt(7)
	v_pk_mul_f32 v[2:3], v[8:9], v[214:215]
	v_pk_mul_f32 v[56:57], v[10:11], v[216:217]
	v_cvt_pk_bf16_f32 v2, v2, v3
	v_cvt_pk_bf16_f32 v3, v56, v57
	ds_write_b64 v103, v[2:3] offset:64
	s_waitcnt lgkmcnt(7)
	v_pk_mul_f32 v[238:239], v[12:13], v[218:219]
	v_pk_mul_f32 v[240:241], v[14:15], v[220:221]
	v_cvt_pk_bf16_f32 v238, v238, v239
	v_cvt_pk_bf16_f32 v239, v240, v241
	ds_write_b64 v103, v[238:239] offset:96
	s_waitcnt lgkmcnt(7)
	v_pk_mul_f32 v[2:3], v[20:21], v[222:223]
	v_pk_mul_f32 v[56:57], v[22:23], v[224:225]
	v_cvt_pk_bf16_f32 v2, v2, v3
	v_cvt_pk_bf16_f32 v3, v56, v57
	ds_write_b64 v103, v[2:3] offset:128
	s_waitcnt lgkmcnt(7)
	v_pk_mul_f32 v[238:239], v[28:29], v[226:227]
	v_pk_mul_f32 v[240:241], v[30:31], v[228:229]
	v_cvt_pk_bf16_f32 v238, v238, v239
	v_cvt_pk_bf16_f32 v239, v240, v241
	ds_write_b64 v103, v[238:239] offset:160
	s_waitcnt lgkmcnt(7)
	v_pk_mul_f32 v[2:3], v[24:25], v[230:231]
	v_pk_mul_f32 v[56:57], v[26:27], v[232:233]
	v_cvt_pk_bf16_f32 v2, v2, v3
	v_cvt_pk_bf16_f32 v3, v56, v57
	ds_write_b64 v103, v[2:3] offset:192
	s_waitcnt lgkmcnt(7)
	v_pk_mul_f32 v[238:239], v[32:33], v[234:235]
	v_pk_mul_f32 v[240:241], v[34:35], v[236:237]
	v_cvt_pk_bf16_f32 v238, v238, v239
	v_cvt_pk_bf16_f32 v239, v240, v241
	ds_write_b64 v103, v[238:239] offset:224
	s_waitcnt lgkmcnt(0)
	s_barrier
	ds_read_b128 v[56:59], v129 offset:32768
	ds_read_b128 v[60:63], v0
	ds_read_b128 v[64:67], v0 offset:64
	ds_read_b128 v[68:71], v129 offset:32832
	s_waitcnt lgkmcnt(2)
	v_mfma_f32_16x16x32_bf16 v[56:59], v[56:59], v[60:63], 0
	ds_read_b128 v[168:171], v129 offset:37120
	ds_read_b128 v[172:175], v129 offset:37184
	s_waitcnt lgkmcnt(2)
	v_mfma_f32_16x16x32_bf16 v[56:59], v[68:71], v[64:67], v[56:59]
	ds_read_b128 v[68:71], v129 offset:32896
	s_waitcnt lgkmcnt(2)
	v_mfma_f32_16x16x32_bf16 v[60:63], v[168:171], v[60:63], 0
	s_waitcnt lgkmcnt(1)
	v_mfma_f32_16x16x32_bf16 v[60:63], v[172:175], v[64:67], v[60:63]
	ds_read_b128 v[64:67], v0 offset:128
	ds_read_b128 v[168:171], v0 offset:192
	ds_read_b128 v[172:175], v129 offset:32960
	s_waitcnt lgkmcnt(2)
	v_mfma_f32_16x16x32_bf16 v[56:59], v[68:71], v[64:67], v[56:59]
	ds_read_b128 v[68:71], v129 offset:37248
	ds_read_b128 v[176:179], v129 offset:37312
	s_waitcnt lgkmcnt(1)
	v_mfma_f32_16x16x32_bf16 v[60:63], v[68:71], v[64:67], v[60:63]
	v_mfma_f32_16x16x32_bf16 v[64:67], v[172:175], v[168:171], v[56:59]
	s_waitcnt lgkmcnt(0)
	v_mfma_f32_16x16x32_bf16 v[60:63], v[176:179], v[168:171], v[60:63]
	s_and_saveexec_b64 s[90:91], s[12:13]
	s_cbranch_execz .LBB0_746
	ds_read_b128 v[56:59], v107 offset:32768
	ds_read_b128 v[68:71], v113 offset:41472
	s_waitcnt lgkmcnt(0)
	v_mfma_f32_16x16x32_bf16 v[56:59], v[56:59], v[68:71], 0
	ds_read_b128 v[68:71], v107 offset:32832
	ds_read_b128 v[168:171], v113 offset:41536
	s_waitcnt lgkmcnt(0)
	v_mfma_f32_16x16x32_bf16 v[56:59], v[68:71], v[168:171], v[56:59]
	ds_read_b128 v[68:71], v107 offset:32896
	ds_read_b128 v[168:171], v113 offset:41600
	s_waitcnt lgkmcnt(0)
	v_mfma_f32_16x16x32_bf16 v[56:59], v[68:71], v[168:171], v[56:59]
	ds_read_b128 v[68:71], v107 offset:32960
	ds_read_b128 v[168:171], v113 offset:41664
	s_waitcnt lgkmcnt(0)
	v_mfma_f32_16x16x32_bf16 v[56:59], v[68:71], v[168:171], v[56:59]
	s_nop 7
	v_cvt_pk_bf16_f32 v0, v56, s0
	v_cndmask_b32_e64 v0, 0, v0, s[88:89]
	ds_write_b16 v130, v0
	v_cvt_pk_bf16_f32 v0, v57, s0
	v_cndmask_b32_e64 v0, 0, v0, s[86:87]
	ds_write_b16 v130, v0 offset:80
	v_cvt_pk_bf16_f32 v0, v58, s0
	v_cndmask_b32_e64 v0, 0, v0, s[84:85]
	ds_write_b16 v130, v0 offset:160
	v_cvt_pk_bf16_f32 v0, v59, s0
	v_cndmask_b32_e64 v0, 0, v0, s[82:83]
	ds_write_b16 v130, v0 offset:240
